# GLA m1/m2: all LDS fragment reads of the MFMA chains hoisted to the section top into free VGPR quads, counted lgkmcnt (MFMA<->LDS interleave, strategy 8)
# baseline (speedup 1.0000x reference)
.LBB0_1045:
	s_waitcnt lgkmcnt(0)
	s_barrier
	ds_read_b64_tr_b16 v[116:117], v77 offset:40960
	ds_read_b64_tr_b16 v[118:119], v77 offset:45568
	ds_read_b64_tr_b16 v[120:121], v77 offset:50176
	ds_read_b64_tr_b16 v[122:123], v77 offset:54784
	ds_read_b64_tr_b16 v[128:129], v78
	ds_read_b64_tr_b16 v[130:131], v78 offset:2560
	ds_read_b64_tr_b16 v[136:137], v78 offset:5120
	ds_read_b64_tr_b16 v[138:139], v78 offset:7680
	ds_read_b64_tr_b16 v[144:145], v78 offset:32
	ds_read_b64_tr_b16 v[146:147], v78 offset:2592
	ds_read_b64_tr_b16 v[148:149], v78 offset:5152
	ds_read_b64_tr_b16 v[150:151], v78 offset:7712
	ds_read_b64_tr_b16 v[152:153], v78 offset:64
	ds_read_b64_tr_b16 v[154:155], v78 offset:2624
	ds_read_b64_tr_b16 v[156:157], v78 offset:5184
	ds_read_b64_tr_b16 v[158:159], v78 offset:7744
	ds_read_b64_tr_b16 v[160:161], v78 offset:96
	ds_read_b64_tr_b16 v[162:163], v78 offset:2656
	ds_read_b64_tr_b16 v[164:165], v78 offset:5216
	ds_read_b64_tr_b16 v[166:167], v78 offset:7776
	ds_read_b64_tr_b16 v[168:169], v78 offset:10240
	ds_read_b64_tr_b16 v[170:171], v78 offset:12800
	ds_read_b64_tr_b16 v[172:173], v78 offset:15360
	ds_read_b64_tr_b16 v[174:175], v78 offset:17920
	ds_read_b64_tr_b16 v[176:177], v78 offset:10272
	ds_read_b64_tr_b16 v[178:179], v78 offset:12832
	ds_read_b64_tr_b16 v[180:181], v78 offset:15392
	ds_read_b64_tr_b16 v[182:183], v78 offset:17952
	ds_read_b64_tr_b16 v[184:185], v78 offset:10304
	ds_read_b64_tr_b16 v[186:187], v78 offset:12864
	ds_read_b64_tr_b16 v[188:189], v78 offset:15424
	ds_read_b64_tr_b16 v[190:191], v78 offset:17984
	ds_read_b64_tr_b16 v[192:193], v78 offset:10336
	ds_read_b64_tr_b16 v[194:195], v78 offset:12896
	ds_read_b64_tr_b16 v[196:197], v78 offset:15456
	ds_read_b64_tr_b16 v[198:199], v78 offset:18016
	s_waitcnt lgkmcnt(15)
	v_mfma_f32_16x16x32_bf16 v[80:83], v[128:131], v[116:119], 0
	s_ashr_i32 s15, s14, 31
	s_lshl_b64 s[2:3], s[14:15], 15
	v_lshl_add_u64 v[68:69], v[66:67], 0, s[2:3]
	s_waitcnt lgkmcnt(15)
	v_mfma_f32_16x16x32_bf16 v[80:83], v[136:139], v[120:123], v[80:83]
	s_add_i32 s22, s22, s40
	s_cmp_lg_u32 s20, s23
	s_mov_b32 s2, s23
	s_nop 4
	v_cvt_pk_bf16_f32 v80, v80, v81
	v_cvt_pk_bf16_f32 v81, v82, v83
	global_store_dwordx2 v[68:69], v[80:81], off
	s_waitcnt lgkmcnt(15)
	v_mfma_f32_16x16x32_bf16 v[80:83], v[144:147], v[116:119], 0
	s_waitcnt lgkmcnt(15)
	v_mfma_f32_16x16x32_bf16 v[80:83], v[148:151], v[120:123], v[80:83]
	s_nop 7
	v_cvt_pk_bf16_f32 v80, v80, v81
	v_cvt_pk_bf16_f32 v81, v82, v83
	global_store_dwordx2 v[68:69], v[80:81], off offset:32
	s_waitcnt lgkmcnt(15)
	v_mfma_f32_16x16x32_bf16 v[80:83], v[152:155], v[116:119], 0
	s_waitcnt lgkmcnt(15)
	v_mfma_f32_16x16x32_bf16 v[80:83], v[156:159], v[120:123], v[80:83]
	s_nop 7
	v_cvt_pk_bf16_f32 v80, v80, v81
	v_cvt_pk_bf16_f32 v81, v82, v83
	global_store_dwordx2 v[68:69], v[80:81], off offset:64
	s_waitcnt lgkmcnt(15)
	v_mfma_f32_16x16x32_bf16 v[80:83], v[160:163], v[116:119], 0
	s_waitcnt lgkmcnt(15)
	v_mfma_f32_16x16x32_bf16 v[80:83], v[164:167], v[120:123], v[80:83]
	s_nop 7
	v_cvt_pk_bf16_f32 v80, v80, v81
	v_cvt_pk_bf16_f32 v81, v82, v83
	global_store_dwordx2 v[68:69], v[80:81], off offset:96
	s_waitcnt lgkmcnt(14)
	v_mfma_f32_16x16x32_bf16 v[80:83], v[168:171], v[116:119], 0
	v_add_co_u32_e32 v68, vcc, s26, v68
	s_waitcnt lgkmcnt(12)
	v_mfma_f32_16x16x32_bf16 v[80:83], v[172:175], v[120:123], v[80:83]
	v_addc_co_u32_e32 v69, vcc, 0, v69, vcc
	s_nop 6
	v_cvt_pk_bf16_f32 v80, v80, v81
	v_cvt_pk_bf16_f32 v81, v82, v83
	global_store_dwordx2 v[68:69], v[80:81], off
	s_waitcnt lgkmcnt(10)
	v_mfma_f32_16x16x32_bf16 v[80:83], v[176:179], v[116:119], 0
	s_waitcnt lgkmcnt(8)
	v_mfma_f32_16x16x32_bf16 v[80:83], v[180:183], v[120:123], v[80:83]
	s_nop 7
	v_cvt_pk_bf16_f32 v80, v80, v81
	v_cvt_pk_bf16_f32 v81, v82, v83
	global_store_dwordx2 v[68:69], v[80:81], off offset:32
	s_waitcnt lgkmcnt(6)
	v_mfma_f32_16x16x32_bf16 v[80:83], v[184:187], v[116:119], 0
	s_waitcnt lgkmcnt(4)
	v_mfma_f32_16x16x32_bf16 v[80:83], v[188:191], v[120:123], v[80:83]
	s_nop 7
	v_cvt_pk_bf16_f32 v80, v80, v81
	v_cvt_pk_bf16_f32 v81, v82, v83
	global_store_dwordx2 v[68:69], v[80:81], off offset:64
	s_waitcnt lgkmcnt(2)
	v_mfma_f32_16x16x32_bf16 v[48:51], v[192:195], v[116:119], 0
	s_waitcnt lgkmcnt(0)
	v_mfma_f32_16x16x32_bf16 v[44:47], v[196:199], v[120:123], v[48:51]
	s_nop 7
	v_cvt_pk_bf16_f32 v44, v44, v45
	v_cvt_pk_bf16_f32 v45, v46, v47
	global_store_dwordx2 v[68:69], v[44:45], off offset:96
	s_cbranch_scc0 .LBB0_1053

.LBB0_1368:
	s_lshl_b32 s2, s52, 7
	s_and_b32 s2, s2, 0x180
	s_lshl_b32 s22, s2, 1
	s_mov_b32 s23, s29
	v_lshl_add_u64 v[36:37], v[72:73], 0, s[22:23]
	s_lshl_b32 s23, s52, 4
	s_and_b32 s2, s23, 0xffffffc0
	v_or_b32_e32 v88, s2, v92
	v_mad_i64_i32 v[38:39], s[2:3], v88, s75, v[36:37]
	v_or_b32_e32 v84, 16, v88
	global_load_dwordx2 v[90:91], v[38:39], off
	v_mad_i64_i32 v[38:39], s[2:3], v84, s75, v[36:37]
	v_or_b32_e32 v80, 32, v88
	v_or_b32_e32 v76, s23, v100
	global_load_dwordx2 v[86:87], v[38:39], off
	v_mad_i64_i32 v[38:39], s[2:3], v80, s75, v[36:37]
	v_mad_i64_i32 v[36:37], s[2:3], v76, s75, v[36:37]
	global_load_dwordx2 v[82:83], v[38:39], off
	global_load_dwordx2 v[78:79], v[36:37], off
	s_waitcnt lgkmcnt(0)
	s_barrier
	ds_read_b128 v[36:39], v104 offset:20480
	ds_read_b128 v[44:47], v104 offset:30720
	ds_read_b128 v[56:59], v105
	ds_read_b128 v[112:115], v105 offset:10240
	ds_read_b128 v[116:119], v104 offset:20544
	ds_read_b128 v[120:123], v104 offset:30784
	ds_read_b128 v[124:127], v105 offset:64
	ds_read_b128 v[128:131], v105 offset:10304
	s_waitcnt lgkmcnt(5)
	v_mfma_f32_16x16x32_bf16 v[36:39], v[36:39], v[56:59], 0
	s_waitcnt lgkmcnt(4)
	v_mfma_f32_16x16x32_bf16 v[44:47], v[44:47], v[112:115], 0
	s_waitcnt lgkmcnt(1)
	v_mfma_f32_16x16x32_bf16 v[36:39], v[116:119], v[124:127], v[36:39]
	s_waitcnt lgkmcnt(0)
	v_mfma_f32_16x16x32_bf16 v[44:47], v[120:123], v[128:131], v[44:47]
	s_nop 7
	v_cndmask_b32_e64 v36, v36, v44, s[4:5]
	v_cndmask_b32_e64 v37, v45, v37, s[6:7]
	v_cndmask_b32_e64 v38, v38, v46, s[8:9]
	v_cndmask_b32_e64 v39, v39, v47, s[10:11]
	v_cvt_pk_bf16_f32 v36, v36, v37
	v_cvt_pk_bf16_f32 v37, v38, v39
	ds_write_b64 v106, v[36:37]
	ds_read_b128 v[36:39], v107 offset:20480
	ds_read_b128 v[44:47], v107 offset:30720
	s_waitcnt lgkmcnt(1)
	v_mfma_f32_16x16x32_bf16 v[36:39], v[36:39], v[56:59], 0
	s_waitcnt lgkmcnt(0)
	v_mfma_f32_16x16x32_bf16 v[44:47], v[44:47], v[112:115], 0
	ds_read_b128 v[56:59], v107 offset:20544
	ds_read_b128 v[112:115], v107 offset:30784
	s_waitcnt lgkmcnt(1)
	v_mfma_f32_16x16x32_bf16 v[36:39], v[56:59], v[124:127], v[36:39]
	s_waitcnt lgkmcnt(0)
	v_mfma_f32_16x16x32_bf16 v[44:47], v[112:115], v[128:131], v[44:47]
	s_nop 7
	v_cndmask_b32_e64 v36, v36, v44, s[12:13]
	v_cndmask_b32_e64 v37, v45, v37, s[14:15]
	v_cndmask_b32_e64 v38, v38, v46, s[16:17]
	v_cndmask_b32_e64 v39, v39, v47, s[18:19]
	v_cvt_pk_bf16_f32 v36, v36, v37
	v_cvt_pk_bf16_f32 v37, v38, v39
	ds_write_b64 v106, v[36:37] offset:8
	s_waitcnt lgkmcnt(0)
	s_barrier
	ds_read_b64_tr_b16 v[112:113], v108 offset:40960
	ds_read_b64_tr_b16 v[114:115], v108 offset:45568
	ds_read_b64_tr_b16 v[116:117], v108 offset:50176
	ds_read_b64_tr_b16 v[118:119], v108 offset:54784
	ds_read_b128 v[136:139], v109
	ds_read_b128 v[140:143], v109 offset:64
	ds_read_b128 v[144:147], v110
	ds_read_b128 v[148:151], v110 offset:10240
	ds_read_b128 v[152:155], v110 offset:64
	ds_read_b128 v[156:159], v110 offset:10304
	ds_read_b128 v[160:163], v109 offset:2624
	ds_read_b128 v[164:167], v109 offset:2560
	ds_read_b128 v[168:171], v110 offset:2560
	ds_read_b128 v[172:175], v110 offset:12800
	ds_read_b128 v[176:179], v110 offset:2624
	ds_read_b128 v[180:183], v110 offset:12864
	ds_read_b128 v[184:187], v109 offset:5184
	ds_read_b128 v[188:191], v109 offset:5120
	ds_read_b128 v[192:195], v110 offset:5120
	ds_read_b128 v[196:199], v110 offset:15360
	ds_read_b128 v[200:203], v110 offset:5184
	ds_read_b128 v[204:207], v110 offset:15424
	ds_read_b128 v[208:211], v109 offset:7680
	ds_read_b128 v[212:215], v109 offset:7744
	ds_read_b128 v[218:221], v110 offset:7680
	ds_read_b128 v[222:225], v110 offset:17920
	ds_read_b128 v[226:229], v110 offset:7744
	ds_read_b128 v[242:245], v110 offset:17984
	s_waitcnt lgkmcnt(15)
	v_mfma_f32_16x16x32_bf16 v[36:39], v[112:115], v[136:139], 0
	s_waitcnt lgkmcnt(15)
	v_mfma_f32_16x16x32_bf16 v[36:39], v[116:119], v[140:143], v[36:39]
	s_waitcnt lgkmcnt(15)
	v_mfma_f32_16x16x32_bf16 v[36:39], v[48:51], v[144:147], v[36:39]
	s_waitcnt lgkmcnt(15)
	v_mfma_f32_16x16x32_bf16 v[36:39], v[52:55], v[148:151], v[36:39]
	s_waitcnt lgkmcnt(15)
	v_mfma_f32_16x16x32_bf16 v[36:39], v[32:35], v[152:155], v[36:39]
	s_waitcnt lgkmcnt(15)
	v_mfma_f32_16x16x32_bf16 v[56:59], v[40:43], v[156:159], v[36:39]
	s_nop 4
	s_waitcnt lgkmcnt(15)
	v_mfma_f32_16x16x32_bf16 v[36:39], v[112:115], v[164:167], 0
	v_mfma_f32_16x16x32_bf16 v[36:39], v[116:119], v[160:163], v[36:39]
	s_waitcnt lgkmcnt(15)
	v_mfma_f32_16x16x32_bf16 v[36:39], v[48:51], v[168:171], v[36:39]
	s_waitcnt lgkmcnt(14)
	v_mfma_f32_16x16x32_bf16 v[36:39], v[52:55], v[172:175], v[36:39]
	s_waitcnt lgkmcnt(13)
	v_mfma_f32_16x16x32_bf16 v[36:39], v[32:35], v[176:179], v[36:39]
	s_waitcnt lgkmcnt(12)
	v_mfma_f32_16x16x32_bf16 v[44:47], v[40:43], v[180:183], v[36:39]
	s_nop 4
	s_waitcnt lgkmcnt(10)
	v_mfma_f32_16x16x32_bf16 v[36:39], v[112:115], v[188:191], 0
	v_mfma_f32_16x16x32_bf16 v[36:39], v[116:119], v[184:187], v[36:39]
	s_waitcnt lgkmcnt(9)
	v_mfma_f32_16x16x32_bf16 v[36:39], v[48:51], v[192:195], v[36:39]
	s_waitcnt lgkmcnt(8)
	v_mfma_f32_16x16x32_bf16 v[36:39], v[52:55], v[196:199], v[36:39]
	s_waitcnt lgkmcnt(7)
	v_mfma_f32_16x16x32_bf16 v[36:39], v[32:35], v[200:203], v[36:39]
	s_waitcnt lgkmcnt(5)
	v_mfma_f32_16x16x32_bf16 v[112:115], v[112:115], v[208:211], 0
	s_waitcnt lgkmcnt(4)
	v_mfma_f32_16x16x32_bf16 v[112:115], v[116:119], v[212:215], v[112:115]
	s_waitcnt lgkmcnt(3)
	v_mfma_f32_16x16x32_bf16 v[48:51], v[48:51], v[218:221], v[112:115]
	s_waitcnt lgkmcnt(2)
	v_mfma_f32_16x16x32_bf16 v[48:51], v[52:55], v[222:225], v[48:51]
	s_nop 0
	s_waitcnt lgkmcnt(1)
	v_mfma_f32_16x16x32_bf16 v[32:35], v[32:35], v[226:229], v[48:51]
	s_nop 2
	v_mul_f32_e64 v48, v56, v56
	v_mul_f32_e64 v49, v57, v57
	v_mfma_f32_16x16x32_bf16 v[36:39], v[40:43], v[204:207], v[36:39]
	v_fmac_f32_e32 v49, v56, v56
	s_waitcnt lgkmcnt(0)
	v_mfma_f32_16x16x32_bf16 v[32:35], v[40:43], v[242:245], v[32:35]
	v_add_f32_e32 v40, 0, v56
	v_add_f32_e32 v40, v57, v40
	v_pk_mul_f32 v[42:43], v[58:59], v[58:59]
	v_add_f32_e32 v40, v58, v40
	v_add_f32_e32 v43, v42, v49
	v_mul_f32_e32 v41, v59, v59
	v_mov_b32_e32 v42, v59
	v_pk_add_f32 v[40:41], v[42:43], v[40:41]
	ds_bpermute_b32 v42, v96, v40
	ds_bpermute_b32 v43, v96, v41
	s_waitcnt lgkmcnt(0)
	v_pk_add_f32 v[40:41], v[40:41], v[42:43]
	ds_bpermute_b32 v42, v97, v40
	ds_bpermute_b32 v43, v97, v41
	s_and_saveexec_b64 s[52:53], vcc
	s_cbranch_execz .LBB0_1370
	s_waitcnt lgkmcnt(0)
	v_pk_add_f32 v[40:41], v[40:41], v[42:43]
	ds_write_b64 v98, v[40:41]
